# pa_mid_burst_setprio_pair_removed
# speedup vs baseline: 1.0005x; 1.0005x over previous
; #define PG8_STAGE(bufoff, gbase, voff) do { _Pragma("unroll") for (int _i = 0; _i < 2; ++_i) \
;         __builtin_amdgcn_global_load_lds((const unsigned*)((const char*)(gbase) + (voff)[_i]), (LAS unsigned*)(lds + (bufoff) + ldsw + _i * 8192), 16, 0, 0); } while (0)
; #define PG8_LDA(dst, b, h) do { _Pragma("unroll") for (int m = 0; m < 4; ++m) _Pragma("unroll") for (int k = 0; k < 2; ++k) dst[m][k] = *(const LAS bf16x8*)(lds + PG8_SA(b, h) + aoff + m * 2048 + k * 1024); } while (0)
; #define PG8_LDB(dst, b, h) do { _Pragma("unroll") for (int n = 0; n < 2; ++n) _Pragma("unroll") for (int k = 0; k < 2; ++k) dst[n][k] = *(const LAS bf16x8*)(lds + PG8_SB(b, h) + boff + n * 2048 + k * 1024); } while (0)
; #define PG8_MMA(ai, bj, At, Bt) do { __builtin_amdgcn_s_setprio(1); _Pragma("unroll") for (int m = 0; m < 4; ++m) _Pragma("unroll") for (int n = 0; n < 2; ++n) _Pragma("unroll") for (int k = 0; k < 2; ++k) \
;         acc[ai][bj][m][n] = __builtin_amdgcn_mfma_f32_16x16x32_bf16(Bt[n][k], At[m][k], acc[ai][bj][m][n], 0, 0, 0); __builtin_amdgcn_s_setprio(0); } while (0)
; #define PG8_WAIT_V(n) asm volatile("s_waitcnt vmcnt(" #n ")" ::: "memory")
; #define PG8_WAIT_L(n) asm volatile("s_waitcnt lgkmcnt(" #n ")" ::: "memory")
; #define PG8_BAR __builtin_amdgcn_s_barrier()
; #define PG8_SCHED __builtin_amdgcn_sched_barrier(0)
; template <class Epi, class Sched>
; __device__ __forceinline__ void gemm_phase(LAS unsigned char* lds, const Sched& S, const Epi& E, bool natural = false) {
;     ...
;             const char* a1 = cA + (size_t)(t + 1) * kstep;
;             const char* a2 = last ? nA : cA + (size_t)(t + 2) * kstep; const char* b2 = last ? nB : cB + (size_t)(t + 2) * kstep;
;             const char* a3 = a2 + kstep; const char* b3 = b2 + kstep;
;             if constexpr (Epi::MIDHOOK) { if (t == nt / 2) E.mid(acc, cur, wr, wc, fr, fq); }
;             PG8_LDB(B0, 0, 0); PG8_LDB(B1, 0, 1); PG8_SCHED; PG8_LDA(At, 0, 0); PG8_STAGE(PG8_SA(1, 1), a1 + hstep, voffA);
;             PG8_WAIT_V(8); PG8_WAIT_L(0); PG8_BAR; PG8_MMA(0, 0, At, B0); PG8_MMA(0, 1, At, B1); PG8_BAR; PG8_SCHED;
;             PG8_LDA(At, 0, 1); PG8_STAGE(PG8_SB(0, 0), b2, voffB0); PG8_STAGE(PG8_SB(0, 1), b2, voffB1); PG8_STAGE(PG8_SA(0, 0), a2, voffA);
;             PG8_WAIT_V(8); PG8_WAIT_L(0); PG8_BAR; PG8_MMA(1, 0, At, B0); PG8_MMA(1, 1, At, B1); PG8_BAR; PG8_SCHED;
.LBB0_173:
	s_add_u32 s40, s40, 0x40080
	s_addc_u32 s41, s41, 0
	s_add_u32 s31, s42, 0x100
	s_addc_u32 s35, s43, 0
	s_mov_b32 s71, -2
	ds_read_b128 v[128:131], v196
	ds_read_b128 v[132:135], v196 offset:1024
	ds_read_b128 v[136:139], v196 offset:2048
	ds_read_b128 v[140:143], v196 offset:3072
	ds_read_b128 v[144:147], v197
	ds_read_b128 v[148:151], v197 offset:1024
	ds_read_b128 v[186:189], v197 offset:2048
	ds_read_b128 v[202:205], v197 offset:3072
	s_add_u32 s42, s40, 0xfffc0080
	s_addc_u32 s43, s41, -1
	s_cmp_eq_u32 s71, 12
	s_cselect_b32 s45, s1, s43
	s_cselect_b32 s44, s0, s42
	s_cselect_b32 s43, s37, s35
	s_cselect_b32 s42, s36, s31
	v_lshl_add_u64 v[238:239], s[40:41], 0, v[178:179]
	s_add_i32 m0, s39, 0xc000
	ds_read_b128 v[206:209], v198
	ds_read_b128 v[210:213], v198 offset:1024
	ds_read_b128 v[214:217], v198 offset:2048
	ds_read_b128 v[218:221], v198 offset:3072
	ds_read_b128 v[222:225], v198 offset:4096
	ds_read_b128 v[226:229], v198 offset:5120
	ds_read_b128 v[230:233], v198 offset:6144
	ds_read_b128 v[234:237], v198 offset:7168
	global_load_lds_dwordx4 v[238:239], off
	v_lshl_add_u64 v[238:239], s[40:41], 0, v[180:181]
	s_add_i32 m0, s39, 0xe000
	s_nop 0
	global_load_lds_dwordx4 v[238:239], off
	s_waitcnt vmcnt(8)
	s_waitcnt lgkmcnt(0)
	s_barrier
	s_setprio 1
	s_waitcnt lgkmcnt(0)
	v_mfma_f32_16x16x32_bf16 v[124:127], v[128:131], v[206:209], 0
	v_mfma_f32_16x16x32_bf16 v[120:123], v[136:139], v[206:209], 0
	v_mfma_f32_16x16x32_bf16 v[108:111], v[128:131], v[214:217], 0
	v_mfma_f32_16x16x32_bf16 v[104:107], v[136:139], v[214:217], 0
	v_mfma_f32_16x16x32_bf16 v[92:95], v[128:131], v[222:225], 0
	v_mfma_f32_16x16x32_bf16 v[88:91], v[136:139], v[222:225], 0
	v_mfma_f32_16x16x32_bf16 v[76:79], v[128:131], v[230:233], 0
	v_mfma_f32_16x16x32_bf16 v[72:75], v[136:139], v[230:233], 0
	v_mfma_f32_16x16x32_bf16 v[124:127], v[132:135], v[210:213], v[124:127]
	v_mfma_f32_16x16x32_bf16 v[120:123], v[140:143], v[210:213], v[120:123]
	v_mfma_f32_16x16x32_bf16 v[108:111], v[132:135], v[218:221], v[108:111]
	v_mfma_f32_16x16x32_bf16 v[104:107], v[140:143], v[218:221], v[104:107]
	v_mfma_f32_16x16x32_bf16 v[92:95], v[132:135], v[226:229], v[92:95]
	v_mfma_f32_16x16x32_bf16 v[88:91], v[140:143], v[226:229], v[88:91]
	v_mfma_f32_16x16x32_bf16 v[76:79], v[132:135], v[234:237], v[76:79]
	v_mfma_f32_16x16x32_bf16 v[72:75], v[140:143], v[234:237], v[72:75]
	v_mfma_f32_16x16x32_bf16 v[116:119], v[144:147], v[206:209], 0
	v_mfma_f32_16x16x32_bf16 v[112:115], v[186:189], v[206:209], 0
	v_mfma_f32_16x16x32_bf16 v[100:103], v[144:147], v[214:217], 0
	v_mfma_f32_16x16x32_bf16 v[96:99], v[186:189], v[214:217], 0
	v_mfma_f32_16x16x32_bf16 v[84:87], v[144:147], v[222:225], 0
	v_mfma_f32_16x16x32_bf16 v[80:83], v[186:189], v[222:225], 0
	v_mfma_f32_16x16x32_bf16 v[68:71], v[144:147], v[230:233], 0
	v_mfma_f32_16x16x32_bf16 v[64:67], v[186:189], v[230:233], 0
	v_mfma_f32_16x16x32_bf16 v[116:119], v[148:151], v[210:213], v[116:119]
	v_mfma_f32_16x16x32_bf16 v[112:115], v[202:205], v[210:213], v[112:115]
	v_mfma_f32_16x16x32_bf16 v[100:103], v[148:151], v[218:221], v[100:103]
	v_mfma_f32_16x16x32_bf16 v[96:99], v[202:205], v[218:221], v[96:99]
	v_mfma_f32_16x16x32_bf16 v[84:87], v[148:151], v[226:229], v[84:87]
	v_mfma_f32_16x16x32_bf16 v[80:83], v[202:205], v[226:229], v[80:83]
	v_mfma_f32_16x16x32_bf16 v[68:71], v[148:151], v[234:237], v[68:71]
	v_mfma_f32_16x16x32_bf16 v[64:67], v[202:205], v[234:237], v[64:67]
	s_setprio 0
	s_barrier
	s_add_i32 s72, s59, s33
	v_lshl_add_u64 v[238:239], s[42:43], 0, v[156:157]
	s_mov_b32 m0, s72
	ds_read_b128 v[206:209], v198 offset:16384
	ds_read_b128 v[210:213], v198 offset:17408
	ds_read_b128 v[214:217], v198 offset:18432
	ds_read_b128 v[218:221], v198 offset:19456
	ds_read_b128 v[222:225], v198 offset:20480
	ds_read_b128 v[226:229], v198 offset:21504
	ds_read_b128 v[230:233], v198 offset:22528
	ds_read_b128 v[234:237], v198 offset:23552
	global_load_lds_dwordx4 v[238:239], off
	v_lshl_add_u64 v[240:241], s[42:43], 0, v[162:163]
	s_add_i32 m0, s72, 0x2000
	s_add_i32 s72, s60, s33
	global_load_lds_dwordx4 v[240:241], off
	v_lshl_add_u64 v[242:243], s[42:43], 0, v[158:159]
	s_mov_b32 m0, s72
	v_lshl_add_u64 v[244:245], s[44:45], 0, v[160:161]
	global_load_lds_dwordx4 v[242:243], off
	v_lshl_add_u64 v[242:243], s[42:43], 0, v[164:165]
	s_add_i32 m0, s72, 0x2000
	s_nop 0
	global_load_lds_dwordx4 v[242:243], off
	v_lshl_add_u64 v[242:243], s[44:45], 0, v[154:155]
	s_mov_b32 m0, s39
	s_nop 0
	global_load_lds_dwordx4 v[242:243], off
	s_mov_b32 m0, s46
	s_nop 0
	global_load_lds_dwordx4 v[244:245], off
	s_waitcnt vmcnt(8)
	s_waitcnt lgkmcnt(0)
	s_barrier
; #define PG8_STAGE(bufoff, gbase, voff) do { _Pragma("unroll") for (int _i = 0; _i < 2; ++_i) \
;         __builtin_amdgcn_global_load_lds((const unsigned*)((const char*)(gbase) + (voff)[_i]), (LAS unsigned*)(lds + (bufoff) + ldsw + _i * 8192), 16, 0, 0); } while (0)
; #define PG8_LDA(dst, b, h) do { _Pragma("unroll") for (int m = 0; m < 4; ++m) _Pragma("unroll") for (int k = 0; k < 2; ++k) dst[m][k] = *(const LAS bf16x8*)(lds + PG8_SA(b, h) + aoff + m * 2048 + k * 1024); } while (0)
; #define PG8_LDB(dst, b, h) do { _Pragma("unroll") for (int n = 0; n < 2; ++n) _Pragma("unroll") for (int k = 0; k < 2; ++k) dst[n][k] = *(const LAS bf16x8*)(lds + PG8_SB(b, h) + boff + n * 2048 + k * 1024); } while (0)
; #define PG8_MMA(ai, bj, At, Bt) do { __builtin_amdgcn_s_setprio(1); _Pragma("unroll") for (int m = 0; m < 4; ++m) _Pragma("unroll") for (int n = 0; n < 2; ++n) _Pragma("unroll") for (int k = 0; k < 2; ++k) \
;         acc[ai][bj][m][n] = __builtin_amdgcn_mfma_f32_16x16x32_bf16(Bt[n][k], At[m][k], acc[ai][bj][m][n], 0, 0, 0); __builtin_amdgcn_s_setprio(0); } while (0)
; #define PG8_WAIT_V(n) asm volatile("s_waitcnt vmcnt(" #n ")" ::: "memory")
; #define PG8_WAIT_L(n) asm volatile("s_waitcnt lgkmcnt(" #n ")" ::: "memory")
; #define PG8_BAR __builtin_amdgcn_s_barrier()
; #define PG8_SCHED __builtin_amdgcn_sched_barrier(0)
; template <class Epi, class Sched>
; __device__ __forceinline__ void gemm_phase(LAS unsigned char* lds, const Sched& S, const Epi& E, bool natural = false) {
;     ...
;             PG8_WAIT_V(8); PG8_WAIT_L(0); PG8_BAR; PG8_MMA(1, 0, At, B0); PG8_MMA(1, 1, At, B1); PG8_BAR; PG8_SCHED;
;             PG8_LDB(B0, 1, 0); PG8_LDB(B1, 1, 1); PG8_SCHED; PG8_LDA(At, 1, 0); PG8_STAGE(PG8_SA(0, 1), a2 + hstep, voffA);
;             PG8_WAIT_V(8); PG8_WAIT_L(0); PG8_BAR; PG8_MMA(0, 0, At, B0); PG8_MMA(0, 1, At, B1); PG8_BAR; PG8_SCHED;
	s_setprio 1
	s_waitcnt lgkmcnt(0)
	v_mfma_f32_16x16x32_bf16 v[60:63], v[128:131], v[206:209], 0
	v_mfma_f32_16x16x32_bf16 v[56:59], v[136:139], v[206:209], 0
	v_mfma_f32_16x16x32_bf16 v[44:47], v[128:131], v[214:217], 0
	v_mfma_f32_16x16x32_bf16 v[40:43], v[136:139], v[214:217], 0
	v_mfma_f32_16x16x32_bf16 v[28:31], v[128:131], v[222:225], 0
	v_mfma_f32_16x16x32_bf16 v[24:27], v[136:139], v[222:225], 0
	v_mfma_f32_16x16x32_bf16 v[12:15], v[128:131], v[230:233], 0
	v_mfma_f32_16x16x32_bf16 v[8:11], v[136:139], v[230:233], 0
	v_mfma_f32_16x16x32_bf16 v[60:63], v[132:135], v[210:213], v[60:63]
	v_mfma_f32_16x16x32_bf16 v[56:59], v[140:143], v[210:213], v[56:59]
	v_mfma_f32_16x16x32_bf16 v[44:47], v[132:135], v[218:221], v[44:47]
	v_mfma_f32_16x16x32_bf16 v[40:43], v[140:143], v[218:221], v[40:43]
	v_mfma_f32_16x16x32_bf16 v[28:31], v[132:135], v[226:229], v[28:31]
	v_mfma_f32_16x16x32_bf16 v[24:27], v[140:143], v[226:229], v[24:27]
	v_mfma_f32_16x16x32_bf16 v[12:15], v[132:135], v[234:237], v[12:15]
	v_mfma_f32_16x16x32_bf16 v[8:11], v[140:143], v[234:237], v[8:11]
	v_mfma_f32_16x16x32_bf16 v[52:55], v[144:147], v[206:209], 0
	v_mfma_f32_16x16x32_bf16 v[48:51], v[186:189], v[206:209], 0
	v_mfma_f32_16x16x32_bf16 v[36:39], v[144:147], v[214:217], 0
	v_mfma_f32_16x16x32_bf16 v[32:35], v[186:189], v[214:217], 0
	v_mfma_f32_16x16x32_bf16 v[20:23], v[144:147], v[222:225], 0
	v_mfma_f32_16x16x32_bf16 v[16:19], v[186:189], v[222:225], 0
	v_mfma_f32_16x16x32_bf16 v[4:7], v[144:147], v[230:233], 0
	v_mfma_f32_16x16x32_bf16 v[0:3], v[186:189], v[230:233], 0
	v_mfma_f32_16x16x32_bf16 v[52:55], v[148:151], v[210:213], v[52:55]
	v_mfma_f32_16x16x32_bf16 v[48:51], v[202:205], v[210:213], v[48:51]
	v_mfma_f32_16x16x32_bf16 v[36:39], v[148:151], v[218:221], v[36:39]
	v_mfma_f32_16x16x32_bf16 v[32:35], v[202:205], v[218:221], v[32:35]
	v_mfma_f32_16x16x32_bf16 v[20:23], v[148:151], v[226:229], v[20:23]
	v_mfma_f32_16x16x32_bf16 v[16:19], v[202:205], v[226:229], v[16:19]
	v_mfma_f32_16x16x32_bf16 v[4:7], v[148:151], v[234:237], v[4:7]
	v_mfma_f32_16x16x32_bf16 v[0:3], v[202:205], v[234:237], v[0:3]
	s_setprio 0
	s_barrier
	s_add_i32 s72, 0, 0x18000
	s_add_i32 s73, 0, 0x1c000
	v_add_u32_e32 v140, s72, v192
	v_add_u32_e32 v166, s73, v192
	ds_read_b128 v[128:131], v140
	ds_read_b128 v[132:135], v140 offset:1024
	ds_read_b128 v[136:139], v140 offset:2048
	ds_read_b128 v[140:143], v140 offset:3072
	ds_read_b128 v[144:147], v166
	ds_read_b128 v[148:151], v166 offset:1024
	ds_read_b128 v[186:189], v166 offset:2048
	ds_read_b128 v[202:205], v166 offset:3072
	s_add_u32 s44, s44, 0x40000
	s_addc_u32 s45, s45, 0
	s_mov_b32 m0, s47
	v_lshl_add_u64 v[246:247], s[44:45], 0, v[154:155]
	ds_read_b128 v[206:209], v198 offset:32768
	ds_read_b128 v[210:213], v198 offset:33792
	ds_read_b128 v[214:217], v198 offset:34816
	ds_read_b128 v[218:221], v198 offset:35840
	ds_read_b128 v[222:225], v198 offset:36864
	ds_read_b128 v[226:229], v198 offset:37888
	ds_read_b128 v[230:233], v198 offset:38912
	ds_read_b128 v[234:237], v198 offset:39936
	global_load_lds_dwordx4 v[246:247], off
	v_lshl_add_u64 v[246:247], s[44:45], 0, v[160:161]
	s_mov_b32 m0, s49
	s_nop 0
	global_load_lds_dwordx4 v[246:247], off
	s_waitcnt vmcnt(8)
	s_waitcnt lgkmcnt(0)
	s_barrier
	s_setprio 1
	s_waitcnt lgkmcnt(0)
	v_mfma_f32_16x16x32_bf16 v[124:127], v[128:131], v[206:209], v[124:127]
	v_mfma_f32_16x16x32_bf16 v[120:123], v[136:139], v[206:209], v[120:123]
	v_mfma_f32_16x16x32_bf16 v[108:111], v[128:131], v[214:217], v[108:111]
	v_mfma_f32_16x16x32_bf16 v[104:107], v[136:139], v[214:217], v[104:107]
	v_mfma_f32_16x16x32_bf16 v[92:95], v[128:131], v[222:225], v[92:95]
	v_mfma_f32_16x16x32_bf16 v[88:91], v[136:139], v[222:225], v[88:91]
	v_mfma_f32_16x16x32_bf16 v[76:79], v[128:131], v[230:233], v[76:79]
	v_mfma_f32_16x16x32_bf16 v[72:75], v[136:139], v[230:233], v[72:75]
	v_mfma_f32_16x16x32_bf16 v[124:127], v[132:135], v[210:213], v[124:127]
	v_mfma_f32_16x16x32_bf16 v[120:123], v[140:143], v[210:213], v[120:123]
	v_mfma_f32_16x16x32_bf16 v[108:111], v[132:135], v[218:221], v[108:111]
	v_mfma_f32_16x16x32_bf16 v[104:107], v[140:143], v[218:221], v[104:107]
	v_mfma_f32_16x16x32_bf16 v[92:95], v[132:135], v[226:229], v[92:95]
	v_mfma_f32_16x16x32_bf16 v[88:91], v[140:143], v[226:229], v[88:91]
	v_mfma_f32_16x16x32_bf16 v[76:79], v[132:135], v[234:237], v[76:79]
	v_mfma_f32_16x16x32_bf16 v[72:75], v[140:143], v[234:237], v[72:75]
	v_mfma_f32_16x16x32_bf16 v[116:119], v[144:147], v[206:209], v[116:119]
	v_mfma_f32_16x16x32_bf16 v[112:115], v[186:189], v[206:209], v[112:115]
	v_mfma_f32_16x16x32_bf16 v[100:103], v[144:147], v[214:217], v[100:103]
	v_mfma_f32_16x16x32_bf16 v[96:99], v[186:189], v[214:217], v[96:99]
	v_mfma_f32_16x16x32_bf16 v[84:87], v[144:147], v[222:225], v[84:87]
	v_mfma_f32_16x16x32_bf16 v[80:83], v[186:189], v[222:225], v[80:83]
	v_mfma_f32_16x16x32_bf16 v[68:71], v[144:147], v[230:233], v[68:71]
	v_mfma_f32_16x16x32_bf16 v[64:67], v[186:189], v[230:233], v[64:67]
	v_mfma_f32_16x16x32_bf16 v[116:119], v[148:151], v[210:213], v[116:119]
	v_mfma_f32_16x16x32_bf16 v[112:115], v[202:205], v[210:213], v[112:115]
	v_mfma_f32_16x16x32_bf16 v[100:103], v[148:151], v[218:221], v[100:103]
	v_mfma_f32_16x16x32_bf16 v[96:99], v[202:205], v[218:221], v[96:99]
	v_mfma_f32_16x16x32_bf16 v[84:87], v[148:151], v[226:229], v[84:87]
	v_mfma_f32_16x16x32_bf16 v[80:83], v[202:205], v[226:229], v[80:83]
	v_mfma_f32_16x16x32_bf16 v[68:71], v[148:151], v[234:237], v[68:71]
	v_mfma_f32_16x16x32_bf16 v[64:67], v[202:205], v[234:237], v[64:67]
	s_setprio 0
	s_barrier
; #define PG8_STAGE(bufoff, gbase, voff) do { _Pragma("unroll") for (int _i = 0; _i < 2; ++_i) \
;         __builtin_amdgcn_global_load_lds((const unsigned*)((const char*)(gbase) + (voff)[_i]), (LAS unsigned*)(lds + (bufoff) + ldsw + _i * 8192), 16, 0, 0); } while (0)
; #define PG8_LDA(dst, b, h) do { _Pragma("unroll") for (int m = 0; m < 4; ++m) _Pragma("unroll") for (int k = 0; k < 2; ++k) dst[m][k] = *(const LAS bf16x8*)(lds + PG8_SA(b, h) + aoff + m * 2048 + k * 1024); } while (0)
; #define PG8_LDB(dst, b, h) do { _Pragma("unroll") for (int n = 0; n < 2; ++n) _Pragma("unroll") for (int k = 0; k < 2; ++k) dst[n][k] = *(const LAS bf16x8*)(lds + PG8_SB(b, h) + boff + n * 2048 + k * 1024); } while (0)
; #define PG8_MMA(ai, bj, At, Bt) do { __builtin_amdgcn_s_setprio(1); _Pragma("unroll") for (int m = 0; m < 4; ++m) _Pragma("unroll") for (int n = 0; n < 2; ++n) _Pragma("unroll") for (int k = 0; k < 2; ++k) \
;         acc[ai][bj][m][n] = __builtin_amdgcn_mfma_f32_16x16x32_bf16(Bt[n][k], At[m][k], acc[ai][bj][m][n], 0, 0, 0); __builtin_amdgcn_s_setprio(0); } while (0)
; #define PG8_WAIT_V(n) asm volatile("s_waitcnt vmcnt(" #n ")" ::: "memory")
; #define PG8_WAIT_L(n) asm volatile("s_waitcnt lgkmcnt(" #n ")" ::: "memory")
; #define PG8_BAR __builtin_amdgcn_s_barrier()
; #define PG8_SCHED __builtin_amdgcn_sched_barrier(0)
; template <class Epi, class Sched>
; __device__ __forceinline__ void gemm_phase(LAS unsigned char* lds, const Sched& S, const Epi& E, bool natural = false) {
;     ...
;             PG8_LDB(B0, 0, 0); PG8_LDB(B1, 0, 1); PG8_SCHED; PG8_LDA(At, 0, 0); PG8_STAGE(PG8_SA(1, 1), a1 + hstep, voffA);
;             PG8_WAIT_V(8); PG8_WAIT_L(0); PG8_BAR; PG8_MMA(0, 0, At, B0); PG8_MMA(0, 1, At, B1); PG8_BAR; PG8_SCHED;
;     ...
;             PG8_LDA(At, 1, 1); PG8_STAGE(PG8_SB(1, 0), b3, voffB0); PG8_STAGE(PG8_SB(1, 1), b3, voffB1); PG8_STAGE(PG8_SA(1, 0), a3, voffA);
;             PG8_WAIT_V(8); PG8_WAIT_L(0); PG8_BAR; PG8_MMA(1, 0, At, B0); PG8_MMA(1, 1, At, B1); PG8_BAR; PG8_SCHED;
;         }
	s_add_u32 s42, s42, 0x80
	s_addc_u32 s43, s43, 0
	s_add_i32 s44, s72, s33
	v_lshl_add_u64 v[238:239], v[238:239], 0, s[12:13]
	s_mov_b32 m0, s44
	ds_read_b128 v[206:209], v198 offset:49152
	ds_read_b128 v[210:213], v198 offset:50176
	ds_read_b128 v[214:217], v198 offset:51200
	ds_read_b128 v[218:221], v198 offset:52224
	ds_read_b128 v[222:225], v198 offset:53248
	ds_read_b128 v[226:229], v198 offset:54272
	ds_read_b128 v[230:233], v198 offset:55296
	ds_read_b128 v[234:237], v198 offset:56320
	global_load_lds_dwordx4 v[238:239], off
	v_lshl_add_u64 v[238:239], v[240:241], 0, s[12:13]
	s_add_i32 m0, s44, 0x2000
	s_add_i32 s44, s73, s33
	global_load_lds_dwordx4 v[238:239], off
	v_lshl_add_u64 v[238:239], s[42:43], 0, v[158:159]
	s_mov_b32 m0, s44
	s_nop 0
	global_load_lds_dwordx4 v[238:239], off
	v_lshl_add_u64 v[238:239], s[42:43], 0, v[164:165]
	s_add_i32 m0, s44, 0x2000
	s_nop 0
	global_load_lds_dwordx4 v[238:239], off
	v_lshl_add_u64 v[238:239], v[242:243], 0, s[12:13]
	s_mov_b32 m0, s51
	s_nop 0
	global_load_lds_dwordx4 v[238:239], off
	v_lshl_add_u64 v[238:239], v[244:245], 0, s[12:13]
	s_mov_b32 m0, s52
	s_nop 0
	global_load_lds_dwordx4 v[238:239], off
	s_waitcnt vmcnt(8)
	s_waitcnt lgkmcnt(0)
	s_barrier
	s_setprio 1
	s_waitcnt lgkmcnt(0)
	v_mfma_f32_16x16x32_bf16 v[60:63], v[128:131], v[206:209], v[60:63]
	v_mfma_f32_16x16x32_bf16 v[56:59], v[136:139], v[206:209], v[56:59]
	v_mfma_f32_16x16x32_bf16 v[44:47], v[128:131], v[214:217], v[44:47]
	v_mfma_f32_16x16x32_bf16 v[40:43], v[136:139], v[214:217], v[40:43]
	v_mfma_f32_16x16x32_bf16 v[28:31], v[128:131], v[222:225], v[28:31]
	v_mfma_f32_16x16x32_bf16 v[24:27], v[136:139], v[222:225], v[24:27]
	v_mfma_f32_16x16x32_bf16 v[12:15], v[128:131], v[230:233], v[12:15]
	v_mfma_f32_16x16x32_bf16 v[8:11], v[136:139], v[230:233], v[8:11]
	v_mfma_f32_16x16x32_bf16 v[60:63], v[132:135], v[210:213], v[60:63]
	v_mfma_f32_16x16x32_bf16 v[56:59], v[140:143], v[210:213], v[56:59]
	v_mfma_f32_16x16x32_bf16 v[44:47], v[132:135], v[218:221], v[44:47]
	v_mfma_f32_16x16x32_bf16 v[40:43], v[140:143], v[218:221], v[40:43]
	v_mfma_f32_16x16x32_bf16 v[28:31], v[132:135], v[226:229], v[28:31]
	v_mfma_f32_16x16x32_bf16 v[24:27], v[140:143], v[226:229], v[24:27]
	v_mfma_f32_16x16x32_bf16 v[12:15], v[132:135], v[234:237], v[12:15]
	v_mfma_f32_16x16x32_bf16 v[8:11], v[140:143], v[234:237], v[8:11]
	v_mfma_f32_16x16x32_bf16 v[52:55], v[144:147], v[206:209], v[52:55]
	v_mfma_f32_16x16x32_bf16 v[48:51], v[186:189], v[206:209], v[48:51]
	v_mfma_f32_16x16x32_bf16 v[36:39], v[144:147], v[214:217], v[36:39]
	v_mfma_f32_16x16x32_bf16 v[32:35], v[186:189], v[214:217], v[32:35]
	v_mfma_f32_16x16x32_bf16 v[20:23], v[144:147], v[222:225], v[20:23]
	v_mfma_f32_16x16x32_bf16 v[16:19], v[186:189], v[222:225], v[16:19]
	v_mfma_f32_16x16x32_bf16 v[4:7], v[144:147], v[230:233], v[4:7]
	v_mfma_f32_16x16x32_bf16 v[0:3], v[186:189], v[230:233], v[0:3]
	v_mfma_f32_16x16x32_bf16 v[52:55], v[148:151], v[210:213], v[52:55]
	v_mfma_f32_16x16x32_bf16 v[48:51], v[202:205], v[210:213], v[48:51]
	v_mfma_f32_16x16x32_bf16 v[36:39], v[148:151], v[218:221], v[36:39]
	v_mfma_f32_16x16x32_bf16 v[32:35], v[202:205], v[218:221], v[32:35]
	v_mfma_f32_16x16x32_bf16 v[20:23], v[148:151], v[226:229], v[20:23]
	v_mfma_f32_16x16x32_bf16 v[16:19], v[202:205], v[226:229], v[16:19]
	v_mfma_f32_16x16x32_bf16 v[4:7], v[148:151], v[234:237], v[4:7]
	v_mfma_f32_16x16x32_bf16 v[0:3], v[202:205], v[234:237], v[0:3]
	s_setprio 0
	s_barrier
	s_add_i32 s71, s71, 2
	s_add_u32 s40, s40, 0x100
	s_addc_u32 s41, s41, 0
	s_add_u32 s31, s31, 0x100
	s_addc_u32 s35, s35, 0
	s_cmp_gt_u32 s71, 13
	s_cbranch_scc0 .LBB0_174
.LBB0_174:
	ds_read_b128 v[128:131], v196
	ds_read_b128 v[132:135], v196 offset:1024
	ds_read_b128 v[136:139], v196 offset:2048
	ds_read_b128 v[140:143], v196 offset:3072
	ds_read_b128 v[144:147], v197
	ds_read_b128 v[148:151], v197 offset:1024
	ds_read_b128 v[186:189], v197 offset:2048
	ds_read_b128 v[202:205], v197 offset:3072
	s_add_u32 s42, s40, 0xfffc0080
	s_addc_u32 s43, s41, -1
	s_cmp_eq_u32 s71, 12
	s_cselect_b32 s45, s1, s43
	s_cselect_b32 s44, s0, s42
	s_cselect_b32 s43, s37, s35
	s_cselect_b32 s42, s36, s31
	v_lshl_add_u64 v[238:239], s[40:41], 0, v[178:179]
	s_add_i32 m0, s39, 0xc000
	ds_read_b128 v[206:209], v198
	ds_read_b128 v[210:213], v198 offset:1024
	ds_read_b128 v[214:217], v198 offset:2048
	ds_read_b128 v[218:221], v198 offset:3072
	ds_read_b128 v[222:225], v198 offset:4096
	ds_read_b128 v[226:229], v198 offset:5120
	ds_read_b128 v[230:233], v198 offset:6144
	ds_read_b128 v[234:237], v198 offset:7168
	global_load_lds_dwordx4 v[238:239], off
	v_lshl_add_u64 v[238:239], s[40:41], 0, v[180:181]
	s_add_i32 m0, s39, 0xe000
	s_nop 0
	global_load_lds_dwordx4 v[238:239], off
	s_waitcnt vmcnt(8)
	s_waitcnt lgkmcnt(0)
	s_barrier
; #define PG8_STAGE(bufoff, gbase, voff) do { _Pragma("unroll") for (int _i = 0; _i < 2; ++_i) \
;         __builtin_amdgcn_global_load_lds((const unsigned*)((const char*)(gbase) + (voff)[_i]), (LAS unsigned*)(lds + (bufoff) + ldsw + _i * 8192), 16, 0, 0); } while (0)
; #define PG8_LDA(dst, b, h) do { _Pragma("unroll") for (int m = 0; m < 4; ++m) _Pragma("unroll") for (int k = 0; k < 2; ++k) dst[m][k] = *(const LAS bf16x8*)(lds + PG8_SA(b, h) + aoff + m * 2048 + k * 1024); } while (0)
; #define PG8_MMA(ai, bj, At, Bt) do { __builtin_amdgcn_s_setprio(1); _Pragma("unroll") for (int m = 0; m < 4; ++m) _Pragma("unroll") for (int n = 0; n < 2; ++n) _Pragma("unroll") for (int k = 0; k < 2; ++k) \
;         acc[ai][bj][m][n] = __builtin_amdgcn_mfma_f32_16x16x32_bf16(Bt[n][k], At[m][k], acc[ai][bj][m][n], 0, 0, 0); __builtin_amdgcn_s_setprio(0); } while (0)
; #define PG8_WAIT_V(n) asm volatile("s_waitcnt vmcnt(" #n ")" ::: "memory")
; #define PG8_WAIT_L(n) asm volatile("s_waitcnt lgkmcnt(" #n ")" ::: "memory")
; #define PG8_BAR __builtin_amdgcn_s_barrier()
; #define PG8_SCHED __builtin_amdgcn_sched_barrier(0)
; template <class Epi, class Sched>
; __device__ __forceinline__ void gemm_phase(LAS unsigned char* lds, const Sched& S, const Epi& E, bool natural = false) {
;     ...
;             PG8_WAIT_V(8); PG8_WAIT_L(0); PG8_BAR; PG8_MMA(0, 0, At, B0); PG8_MMA(0, 1, At, B1); PG8_BAR; PG8_SCHED;
;             PG8_LDA(At, 0, 1); PG8_STAGE(PG8_SB(0, 0), b2, voffB0); PG8_STAGE(PG8_SB(0, 1), b2, voffB1); PG8_STAGE(PG8_SA(0, 0), a2, voffA);
;             PG8_WAIT_V(8); PG8_WAIT_L(0); PG8_BAR; PG8_MMA(1, 0, At, B0); PG8_MMA(1, 1, At, B1); PG8_BAR; PG8_SCHED;
	s_setprio 1
	s_waitcnt lgkmcnt(0)
	v_mfma_f32_16x16x32_bf16 v[124:127], v[128:131], v[206:209], v[124:127]
	v_mfma_f32_16x16x32_bf16 v[120:123], v[136:139], v[206:209], v[120:123]
	v_mfma_f32_16x16x32_bf16 v[108:111], v[128:131], v[214:217], v[108:111]
	v_mfma_f32_16x16x32_bf16 v[104:107], v[136:139], v[214:217], v[104:107]
	v_mfma_f32_16x16x32_bf16 v[92:95], v[128:131], v[222:225], v[92:95]
	v_mfma_f32_16x16x32_bf16 v[88:91], v[136:139], v[222:225], v[88:91]
	v_mfma_f32_16x16x32_bf16 v[76:79], v[128:131], v[230:233], v[76:79]
	v_mfma_f32_16x16x32_bf16 v[72:75], v[136:139], v[230:233], v[72:75]
	v_mfma_f32_16x16x32_bf16 v[124:127], v[132:135], v[210:213], v[124:127]
	v_mfma_f32_16x16x32_bf16 v[120:123], v[140:143], v[210:213], v[120:123]
	v_mfma_f32_16x16x32_bf16 v[108:111], v[132:135], v[218:221], v[108:111]
	v_mfma_f32_16x16x32_bf16 v[104:107], v[140:143], v[218:221], v[104:107]
	v_mfma_f32_16x16x32_bf16 v[92:95], v[132:135], v[226:229], v[92:95]
	v_mfma_f32_16x16x32_bf16 v[88:91], v[140:143], v[226:229], v[88:91]
	v_mfma_f32_16x16x32_bf16 v[76:79], v[132:135], v[234:237], v[76:79]
	v_mfma_f32_16x16x32_bf16 v[72:75], v[140:143], v[234:237], v[72:75]
	v_mfma_f32_16x16x32_bf16 v[116:119], v[144:147], v[206:209], v[116:119]
	v_mfma_f32_16x16x32_bf16 v[112:115], v[186:189], v[206:209], v[112:115]
	v_mfma_f32_16x16x32_bf16 v[100:103], v[144:147], v[214:217], v[100:103]
	v_mfma_f32_16x16x32_bf16 v[96:99], v[186:189], v[214:217], v[96:99]
	v_mfma_f32_16x16x32_bf16 v[84:87], v[144:147], v[222:225], v[84:87]
	v_mfma_f32_16x16x32_bf16 v[80:83], v[186:189], v[222:225], v[80:83]
	v_mfma_f32_16x16x32_bf16 v[68:71], v[144:147], v[230:233], v[68:71]
	v_mfma_f32_16x16x32_bf16 v[64:67], v[186:189], v[230:233], v[64:67]
	v_mfma_f32_16x16x32_bf16 v[116:119], v[148:151], v[210:213], v[116:119]
	v_mfma_f32_16x16x32_bf16 v[112:115], v[202:205], v[210:213], v[112:115]
	v_mfma_f32_16x16x32_bf16 v[100:103], v[148:151], v[218:221], v[100:103]
	v_mfma_f32_16x16x32_bf16 v[96:99], v[202:205], v[218:221], v[96:99]
	v_mfma_f32_16x16x32_bf16 v[84:87], v[148:151], v[226:229], v[84:87]
	v_mfma_f32_16x16x32_bf16 v[80:83], v[202:205], v[226:229], v[80:83]
	v_mfma_f32_16x16x32_bf16 v[68:71], v[148:151], v[234:237], v[68:71]
	v_mfma_f32_16x16x32_bf16 v[64:67], v[202:205], v[234:237], v[64:67]
	s_setprio 0
	s_barrier
	s_add_i32 s72, s59, s33
	v_lshl_add_u64 v[238:239], s[42:43], 0, v[156:157]
	s_mov_b32 m0, s72
	ds_read_b128 v[206:209], v198 offset:16384
	ds_read_b128 v[210:213], v198 offset:17408
	ds_read_b128 v[214:217], v198 offset:18432
	ds_read_b128 v[218:221], v198 offset:19456
	ds_read_b128 v[222:225], v198 offset:20480
	ds_read_b128 v[226:229], v198 offset:21504
	ds_read_b128 v[230:233], v198 offset:22528
	ds_read_b128 v[234:237], v198 offset:23552
	global_load_lds_dwordx4 v[238:239], off
	v_lshl_add_u64 v[240:241], s[42:43], 0, v[162:163]
	s_add_i32 m0, s72, 0x2000
	s_add_i32 s72, s60, s33
	global_load_lds_dwordx4 v[240:241], off
	v_lshl_add_u64 v[242:243], s[42:43], 0, v[158:159]
	s_mov_b32 m0, s72
	v_lshl_add_u64 v[244:245], s[44:45], 0, v[160:161]
	global_load_lds_dwordx4 v[242:243], off
	v_lshl_add_u64 v[242:243], s[42:43], 0, v[164:165]
	s_add_i32 m0, s72, 0x2000
	s_nop 0
	global_load_lds_dwordx4 v[242:243], off
	v_lshl_add_u64 v[242:243], s[44:45], 0, v[154:155]
	s_mov_b32 m0, s39
	s_nop 0
	global_load_lds_dwordx4 v[242:243], off
	s_mov_b32 m0, s46
	s_nop 0
	global_load_lds_dwordx4 v[244:245], off
	s_waitcnt vmcnt(8)
	s_waitcnt lgkmcnt(0)
	s_barrier
	s_setprio 1
	s_waitcnt lgkmcnt(0)
	v_mfma_f32_16x16x32_bf16 v[60:63], v[128:131], v[206:209], v[60:63]
	v_mfma_f32_16x16x32_bf16 v[56:59], v[136:139], v[206:209], v[56:59]
	v_mfma_f32_16x16x32_bf16 v[44:47], v[128:131], v[214:217], v[44:47]
	v_mfma_f32_16x16x32_bf16 v[40:43], v[136:139], v[214:217], v[40:43]
	v_mfma_f32_16x16x32_bf16 v[28:31], v[128:131], v[222:225], v[28:31]
	v_mfma_f32_16x16x32_bf16 v[24:27], v[136:139], v[222:225], v[24:27]
	v_mfma_f32_16x16x32_bf16 v[12:15], v[128:131], v[230:233], v[12:15]
	v_mfma_f32_16x16x32_bf16 v[8:11], v[136:139], v[230:233], v[8:11]
	v_mfma_f32_16x16x32_bf16 v[60:63], v[132:135], v[210:213], v[60:63]
	v_mfma_f32_16x16x32_bf16 v[56:59], v[140:143], v[210:213], v[56:59]
	v_mfma_f32_16x16x32_bf16 v[44:47], v[132:135], v[218:221], v[44:47]
	v_mfma_f32_16x16x32_bf16 v[40:43], v[140:143], v[218:221], v[40:43]
	v_mfma_f32_16x16x32_bf16 v[28:31], v[132:135], v[226:229], v[28:31]
	v_mfma_f32_16x16x32_bf16 v[24:27], v[140:143], v[226:229], v[24:27]
	v_mfma_f32_16x16x32_bf16 v[12:15], v[132:135], v[234:237], v[12:15]
	v_mfma_f32_16x16x32_bf16 v[8:11], v[140:143], v[234:237], v[8:11]
	v_mfma_f32_16x16x32_bf16 v[52:55], v[144:147], v[206:209], v[52:55]
	v_mfma_f32_16x16x32_bf16 v[48:51], v[186:189], v[206:209], v[48:51]
	v_mfma_f32_16x16x32_bf16 v[36:39], v[144:147], v[214:217], v[36:39]
	v_mfma_f32_16x16x32_bf16 v[32:35], v[186:189], v[214:217], v[32:35]
	v_mfma_f32_16x16x32_bf16 v[20:23], v[144:147], v[222:225], v[20:23]
	v_mfma_f32_16x16x32_bf16 v[16:19], v[186:189], v[222:225], v[16:19]
	v_mfma_f32_16x16x32_bf16 v[4:7], v[144:147], v[230:233], v[4:7]
	v_mfma_f32_16x16x32_bf16 v[0:3], v[186:189], v[230:233], v[0:3]
	v_mfma_f32_16x16x32_bf16 v[52:55], v[148:151], v[210:213], v[52:55]
	v_mfma_f32_16x16x32_bf16 v[48:51], v[202:205], v[210:213], v[48:51]
	v_mfma_f32_16x16x32_bf16 v[36:39], v[148:151], v[218:221], v[36:39]
	v_mfma_f32_16x16x32_bf16 v[32:35], v[202:205], v[218:221], v[32:35]
	v_mfma_f32_16x16x32_bf16 v[20:23], v[148:151], v[226:229], v[20:23]
	v_mfma_f32_16x16x32_bf16 v[16:19], v[202:205], v[226:229], v[16:19]
	v_mfma_f32_16x16x32_bf16 v[4:7], v[148:151], v[234:237], v[4:7]
	v_mfma_f32_16x16x32_bf16 v[0:3], v[202:205], v[234:237], v[0:3]
	s_setprio 0
	s_barrier
; #define PG8_STAGE(bufoff, gbase, voff) do { _Pragma("unroll") for (int _i = 0; _i < 2; ++_i) \
;         __builtin_amdgcn_global_load_lds((const unsigned*)((const char*)(gbase) + (voff)[_i]), (LAS unsigned*)(lds + (bufoff) + ldsw + _i * 8192), 16, 0, 0); } while (0)
; #define PG8_LDA(dst, b, h) do { _Pragma("unroll") for (int m = 0; m < 4; ++m) _Pragma("unroll") for (int k = 0; k < 2; ++k) dst[m][k] = *(const LAS bf16x8*)(lds + PG8_SA(b, h) + aoff + m * 2048 + k * 1024); } while (0)
; #define PG8_LDB(dst, b, h) do { _Pragma("unroll") for (int n = 0; n < 2; ++n) _Pragma("unroll") for (int k = 0; k < 2; ++k) dst[n][k] = *(const LAS bf16x8*)(lds + PG8_SB(b, h) + boff + n * 2048 + k * 1024); } while (0)
; #define PG8_MMA(ai, bj, At, Bt) do { __builtin_amdgcn_s_setprio(1); _Pragma("unroll") for (int m = 0; m < 4; ++m) _Pragma("unroll") for (int n = 0; n < 2; ++n) _Pragma("unroll") for (int k = 0; k < 2; ++k) \
;         acc[ai][bj][m][n] = __builtin_amdgcn_mfma_f32_16x16x32_bf16(Bt[n][k], At[m][k], acc[ai][bj][m][n], 0, 0, 0); __builtin_amdgcn_s_setprio(0); } while (0)
; #define PG8_WAIT_V(n) asm volatile("s_waitcnt vmcnt(" #n ")" ::: "memory")
; #define PG8_WAIT_L(n) asm volatile("s_waitcnt lgkmcnt(" #n ")" ::: "memory")
; #define PG8_BAR __builtin_amdgcn_s_barrier()
; #define PG8_SCHED __builtin_amdgcn_sched_barrier(0)
; template <class Epi, class Sched>
; __device__ __forceinline__ void gemm_phase(LAS unsigned char* lds, const Sched& S, const Epi& E, bool natural = false) {
;     ...
;             PG8_LDB(B0, 1, 0); PG8_LDB(B1, 1, 1); PG8_SCHED; PG8_LDA(At, 1, 0); PG8_STAGE(PG8_SA(0, 1), a2 + hstep, voffA);
;             PG8_WAIT_V(8); PG8_WAIT_L(0); PG8_BAR; PG8_MMA(0, 0, At, B0); PG8_MMA(0, 1, At, B1); PG8_BAR; PG8_SCHED;
	s_add_i32 s72, 0, 0x18000
	s_add_i32 s73, 0, 0x1c000
	v_add_u32_e32 v140, s72, v192
	v_add_u32_e32 v166, s73, v192
	ds_read_b128 v[128:131], v140
	ds_read_b128 v[132:135], v140 offset:1024
	ds_read_b128 v[136:139], v140 offset:2048
	ds_read_b128 v[140:143], v140 offset:3072
	ds_read_b128 v[144:147], v166
	ds_read_b128 v[148:151], v166 offset:1024
	ds_read_b128 v[186:189], v166 offset:2048
	ds_read_b128 v[202:205], v166 offset:3072
	s_add_u32 s44, s44, 0x40000
	s_addc_u32 s45, s45, 0
	s_mov_b32 m0, s47
	v_lshl_add_u64 v[246:247], s[44:45], 0, v[154:155]
	ds_read_b128 v[206:209], v198 offset:32768
	ds_read_b128 v[210:213], v198 offset:33792
	ds_read_b128 v[214:217], v198 offset:34816
	ds_read_b128 v[218:221], v198 offset:35840
	ds_read_b128 v[222:225], v198 offset:36864
	ds_read_b128 v[226:229], v198 offset:37888
	ds_read_b128 v[230:233], v198 offset:38912
	ds_read_b128 v[234:237], v198 offset:39936
	global_load_lds_dwordx4 v[246:247], off
	v_lshl_add_u64 v[246:247], s[44:45], 0, v[160:161]
	s_mov_b32 m0, s49
	s_nop 0
	global_load_lds_dwordx4 v[246:247], off
	s_waitcnt vmcnt(8)
	s_waitcnt lgkmcnt(0)
	s_barrier
	s_setprio 1
	s_waitcnt lgkmcnt(0)
	v_mfma_f32_16x16x32_bf16 v[124:127], v[128:131], v[206:209], v[124:127]
	v_mfma_f32_16x16x32_bf16 v[120:123], v[136:139], v[206:209], v[120:123]
	v_mfma_f32_16x16x32_bf16 v[108:111], v[128:131], v[214:217], v[108:111]
	v_mfma_f32_16x16x32_bf16 v[104:107], v[136:139], v[214:217], v[104:107]
	v_mfma_f32_16x16x32_bf16 v[92:95], v[128:131], v[222:225], v[92:95]
	v_mfma_f32_16x16x32_bf16 v[88:91], v[136:139], v[222:225], v[88:91]
	v_mfma_f32_16x16x32_bf16 v[76:79], v[128:131], v[230:233], v[76:79]
	v_mfma_f32_16x16x32_bf16 v[72:75], v[136:139], v[230:233], v[72:75]
	v_mfma_f32_16x16x32_bf16 v[124:127], v[132:135], v[210:213], v[124:127]
	v_mfma_f32_16x16x32_bf16 v[120:123], v[140:143], v[210:213], v[120:123]
	v_mfma_f32_16x16x32_bf16 v[108:111], v[132:135], v[218:221], v[108:111]
	v_mfma_f32_16x16x32_bf16 v[104:107], v[140:143], v[218:221], v[104:107]
	v_mfma_f32_16x16x32_bf16 v[92:95], v[132:135], v[226:229], v[92:95]
	v_mfma_f32_16x16x32_bf16 v[88:91], v[140:143], v[226:229], v[88:91]
	v_mfma_f32_16x16x32_bf16 v[76:79], v[132:135], v[234:237], v[76:79]
	v_mfma_f32_16x16x32_bf16 v[72:75], v[140:143], v[234:237], v[72:75]
	v_mfma_f32_16x16x32_bf16 v[116:119], v[144:147], v[206:209], v[116:119]
	v_mfma_f32_16x16x32_bf16 v[112:115], v[186:189], v[206:209], v[112:115]
	v_mfma_f32_16x16x32_bf16 v[100:103], v[144:147], v[214:217], v[100:103]
	v_mfma_f32_16x16x32_bf16 v[96:99], v[186:189], v[214:217], v[96:99]
	v_mfma_f32_16x16x32_bf16 v[84:87], v[144:147], v[222:225], v[84:87]
	v_mfma_f32_16x16x32_bf16 v[80:83], v[186:189], v[222:225], v[80:83]
	v_mfma_f32_16x16x32_bf16 v[68:71], v[144:147], v[230:233], v[68:71]
	v_mfma_f32_16x16x32_bf16 v[64:67], v[186:189], v[230:233], v[64:67]
	v_mfma_f32_16x16x32_bf16 v[116:119], v[148:151], v[210:213], v[116:119]
	v_mfma_f32_16x16x32_bf16 v[112:115], v[202:205], v[210:213], v[112:115]
	v_mfma_f32_16x16x32_bf16 v[100:103], v[148:151], v[218:221], v[100:103]
	v_mfma_f32_16x16x32_bf16 v[96:99], v[202:205], v[218:221], v[96:99]
	v_mfma_f32_16x16x32_bf16 v[84:87], v[148:151], v[226:229], v[84:87]
	v_mfma_f32_16x16x32_bf16 v[80:83], v[202:205], v[226:229], v[80:83]
	v_mfma_f32_16x16x32_bf16 v[68:71], v[148:151], v[234:237], v[68:71]
	v_mfma_f32_16x16x32_bf16 v[64:67], v[202:205], v[234:237], v[64:67]
	s_setprio 0
	s_barrier
; #define PG8_STAGE(bufoff, gbase, voff) do { _Pragma("unroll") for (int _i = 0; _i < 2; ++_i) \
;         __builtin_amdgcn_global_load_lds((const unsigned*)((const char*)(gbase) + (voff)[_i]), (LAS unsigned*)(lds + (bufoff) + ldsw + _i * 8192), 16, 0, 0); } while (0)
; #define PG8_LDA(dst, b, h) do { _Pragma("unroll") for (int m = 0; m < 4; ++m) _Pragma("unroll") for (int k = 0; k < 2; ++k) dst[m][k] = *(const LAS bf16x8*)(lds + PG8_SA(b, h) + aoff + m * 2048 + k * 1024); } while (0)
; #define PG8_MMA(ai, bj, At, Bt) do { __builtin_amdgcn_s_setprio(1); _Pragma("unroll") for (int m = 0; m < 4; ++m) _Pragma("unroll") for (int n = 0; n < 2; ++n) _Pragma("unroll") for (int k = 0; k < 2; ++k) \
;         acc[ai][bj][m][n] = __builtin_amdgcn_mfma_f32_16x16x32_bf16(Bt[n][k], At[m][k], acc[ai][bj][m][n], 0, 0, 0); __builtin_amdgcn_s_setprio(0); } while (0)
; #define PG8_WAIT_V(n) asm volatile("s_waitcnt vmcnt(" #n ")" ::: "memory")
; #define PG8_WAIT_L(n) asm volatile("s_waitcnt lgkmcnt(" #n ")" ::: "memory")
; #define PG8_BAR __builtin_amdgcn_s_barrier()
; #define PG8_SCHED __builtin_amdgcn_sched_barrier(0)
; template <class Epi, class Sched>
; __device__ __forceinline__ void gemm_phase(LAS unsigned char* lds, const Sched& S, const Epi& E, bool natural = false) {
;     ...
;             PG8_LDA(At, 1, 1); PG8_STAGE(PG8_SB(1, 0), b3, voffB0); PG8_STAGE(PG8_SB(1, 1), b3, voffB1); PG8_STAGE(PG8_SA(1, 0), a3, voffA);
;             PG8_WAIT_V(8); PG8_WAIT_L(0); PG8_BAR; PG8_MMA(1, 0, At, B0); PG8_MMA(1, 1, At, B1); PG8_BAR; PG8_SCHED;
;         }
;         if (wr == 0) PG8_BAR;
	s_add_u32 s42, s42, 0x80
	s_addc_u32 s43, s43, 0
	s_add_i32 s44, s72, s33
	v_lshl_add_u64 v[238:239], v[238:239], 0, s[12:13]
	s_mov_b32 m0, s44
	ds_read_b128 v[206:209], v198 offset:49152
	ds_read_b128 v[210:213], v198 offset:50176
	ds_read_b128 v[214:217], v198 offset:51200
	ds_read_b128 v[218:221], v198 offset:52224
	ds_read_b128 v[222:225], v198 offset:53248
	ds_read_b128 v[226:229], v198 offset:54272
	ds_read_b128 v[230:233], v198 offset:55296
	ds_read_b128 v[234:237], v198 offset:56320
	global_load_lds_dwordx4 v[238:239], off
	v_lshl_add_u64 v[238:239], v[240:241], 0, s[12:13]
	s_add_i32 m0, s44, 0x2000
	s_add_i32 s44, s73, s33
	global_load_lds_dwordx4 v[238:239], off
	v_lshl_add_u64 v[238:239], s[42:43], 0, v[158:159]
	s_mov_b32 m0, s44
	s_nop 0
	global_load_lds_dwordx4 v[238:239], off
	v_lshl_add_u64 v[238:239], s[42:43], 0, v[164:165]
	s_add_i32 m0, s44, 0x2000
	s_nop 0
	global_load_lds_dwordx4 v[238:239], off
	v_lshl_add_u64 v[238:239], v[242:243], 0, s[12:13]
	s_mov_b32 m0, s51
	s_nop 0
	global_load_lds_dwordx4 v[238:239], off
	v_lshl_add_u64 v[238:239], v[244:245], 0, s[12:13]
	s_mov_b32 m0, s52
	s_nop 0
	global_load_lds_dwordx4 v[238:239], off
	s_waitcnt vmcnt(8)
	s_waitcnt lgkmcnt(0)
	s_barrier
	s_setprio 1
	s_waitcnt lgkmcnt(0)
	v_mfma_f32_16x16x32_bf16 v[60:63], v[128:131], v[206:209], v[60:63]
	v_mfma_f32_16x16x32_bf16 v[56:59], v[136:139], v[206:209], v[56:59]
	v_mfma_f32_16x16x32_bf16 v[44:47], v[128:131], v[214:217], v[44:47]
	v_mfma_f32_16x16x32_bf16 v[40:43], v[136:139], v[214:217], v[40:43]
	v_mfma_f32_16x16x32_bf16 v[28:31], v[128:131], v[222:225], v[28:31]
	v_mfma_f32_16x16x32_bf16 v[24:27], v[136:139], v[222:225], v[24:27]
	v_mfma_f32_16x16x32_bf16 v[12:15], v[128:131], v[230:233], v[12:15]
	v_mfma_f32_16x16x32_bf16 v[8:11], v[136:139], v[230:233], v[8:11]
	v_mfma_f32_16x16x32_bf16 v[60:63], v[132:135], v[210:213], v[60:63]
	v_mfma_f32_16x16x32_bf16 v[56:59], v[140:143], v[210:213], v[56:59]
	v_mfma_f32_16x16x32_bf16 v[44:47], v[132:135], v[218:221], v[44:47]
	v_mfma_f32_16x16x32_bf16 v[40:43], v[140:143], v[218:221], v[40:43]
	v_mfma_f32_16x16x32_bf16 v[28:31], v[132:135], v[226:229], v[28:31]
	v_mfma_f32_16x16x32_bf16 v[24:27], v[140:143], v[226:229], v[24:27]
	v_mfma_f32_16x16x32_bf16 v[12:15], v[132:135], v[234:237], v[12:15]
	v_mfma_f32_16x16x32_bf16 v[8:11], v[140:143], v[234:237], v[8:11]
	v_mfma_f32_16x16x32_bf16 v[52:55], v[144:147], v[206:209], v[52:55]
	v_mfma_f32_16x16x32_bf16 v[48:51], v[186:189], v[206:209], v[48:51]
	v_mfma_f32_16x16x32_bf16 v[36:39], v[144:147], v[214:217], v[36:39]
	v_mfma_f32_16x16x32_bf16 v[32:35], v[186:189], v[214:217], v[32:35]
	v_mfma_f32_16x16x32_bf16 v[20:23], v[144:147], v[222:225], v[20:23]
	v_mfma_f32_16x16x32_bf16 v[16:19], v[186:189], v[222:225], v[16:19]
	v_mfma_f32_16x16x32_bf16 v[4:7], v[144:147], v[230:233], v[4:7]
	v_mfma_f32_16x16x32_bf16 v[0:3], v[186:189], v[230:233], v[0:3]
	v_mfma_f32_16x16x32_bf16 v[52:55], v[148:151], v[210:213], v[52:55]
	v_mfma_f32_16x16x32_bf16 v[48:51], v[202:205], v[210:213], v[48:51]
	v_mfma_f32_16x16x32_bf16 v[36:39], v[148:151], v[218:221], v[36:39]
	v_mfma_f32_16x16x32_bf16 v[32:35], v[202:205], v[218:221], v[32:35]
	v_mfma_f32_16x16x32_bf16 v[20:23], v[148:151], v[226:229], v[20:23]
	v_mfma_f32_16x16x32_bf16 v[16:19], v[202:205], v[226:229], v[16:19]
	v_mfma_f32_16x16x32_bf16 v[4:7], v[148:151], v[234:237], v[4:7]
	v_mfma_f32_16x16x32_bf16 v[0:3], v[202:205], v[234:237], v[0:3]
	s_setprio 0
	s_barrier
	s_add_i32 s71, s71, 2
	s_add_u32 s40, s40, 0x100
	s_addc_u32 s41, s41, 0
	s_add_u32 s31, s31, 0x100
	s_addc_u32 s35, s35, 0
	s_cmp_gt_u32 s71, 13
	s_cbranch_scc0 .LBB0_174
	s_and_b64 vcc, exec, s[14:15]
	s_cbranch_vccz .LBB0_179
	s_barrier
	s_branch .LBB0_179
